# ph8 EpiResid: round 3/4 residual loads prefetched one round early into dead fragment regs, counted waits instead of vmcnt(0) drains
# baseline (speedup 1.0000x reference)
.LBB0_1319:
	v_mov_b32_e32 v66, v179
	s_lshl_b32 s1, s88, 8
	v_bfe_u32 v0, v66, 6, 2
	v_and_b32_e32 v225, 15, v66
	v_bfe_u32 v224, v66, 4, 2
	v_ashrrev_i32_e32 v66, 2, v66
	v_and_b32_e32 v66, 0xffffffc0, v66
	v_lshl_add_u32 v164, s0, 8, v66
	v_lshlrev_b32_e32 v66, 5, v0
	v_lshlrev_b32_e32 v67, 3, v224
	v_or3_b32 v216, v66, s1, v67
	s_add_i32 s1, s0, -16
	s_lshr_b32 s1, s1, 3
	s_add_i32 s1, s1, 1
	s_cmp_lt_i32 s0, 16
	s_cselect_b32 s0, 0, s1
	s_mul_i32 s19, s0, 0x6000
	s_mul_hi_u32 s18, s0, 0x6000
	s_cselect_b32 s1, s43, s86
	s_cselect_b32 s0, s42, s85
	s_add_u32 s2, s73, s19
	v_ashrrev_i32_e32 v217, 31, v216
	s_addc_u32 s3, s78, s18
	v_lshlrev_b64 v[162:163], 2, v[216:217]
	v_lshl_add_u64 v[154:155], s[2:3], 0, v[162:163]
	s_add_u32 s2, s79, s19
	s_addc_u32 s3, s80, s18
	v_lshl_add_u64 v[156:157], s[30:31], 0, v[162:163]
	v_lshl_add_u64 v[158:159], s[2:3], 0, v[162:163]
	global_load_dwordx4 v[74:77], v[154:155], off offset:16
	global_load_dwordx4 v[78:81], v[154:155], off
	global_load_dwordx4 v[66:69], v[156:157], off offset:16
	global_load_dwordx4 v[70:73], v[156:157], off
	global_load_dwordx4 v[146:149], v[158:159], off offset:16
	global_load_dwordx4 v[150:153], v[158:159], off
	v_or_b32_e32 v198, v164, v225
	v_ashrrev_i32_e32 v199, 31, v198
	v_lshl_add_u64 v[220:221], s[0:1], 0, v[162:163]
	v_or_b32_e32 v218, 16, v198
	v_ashrrev_i32_e32 v219, 31, v218
	v_lshlrev_b64 v[248:249], 10, v[198:199]
	v_lshl_add_u64 v[248:249], v[248:249], 0, v[216:217]
	v_cmp_eq_u32_e32 vcc, 0, v224
	s_waitcnt vmcnt(0)
	v_pk_add_f32 v[152:153], v[152:153], 1.0 op_sel_hi:[1,0]
	v_pk_add_f32 v[150:151], v[150:151], 1.0 op_sel_hi:[1,0]
	v_pk_mul_f32 v[208:209], v[72:73], v[152:153]
	v_pk_mul_f32 v[210:211], v[70:71], v[150:151]
	v_pk_add_f32 v[70:71], v[148:149], 1.0 op_sel_hi:[1,0]
	v_pk_add_f32 v[72:73], v[146:147], 1.0 op_sel_hi:[1,0]
	v_pk_mul_f32 v[212:213], v[68:69], v[70:71]
	v_pk_mul_f32 v[214:215], v[66:67], v[72:73]
	global_load_dwordx4 v[66:69], v[154:155], off offset:528
	global_load_dwordx4 v[70:73], v[154:155], off offset:512
	global_load_dwordx4 v[146:149], v[156:157], off offset:528
	global_load_dwordx4 v[150:153], v[156:157], off offset:512
	s_nop 0
	global_load_dwordx4 v[154:157], v[158:159], off offset:528
	s_nop 0
	global_load_dwordx4 v[158:161], v[158:159], off offset:512
	s_waitcnt vmcnt(0)
	v_pk_add_f32 v[160:161], v[160:161], 1.0 op_sel_hi:[1,0]
	s_nop 0
	v_pk_mul_f32 v[200:201], v[152:153], v[160:161]
	v_pk_add_f32 v[152:153], v[154:155], 1.0 op_sel_hi:[1,0]
	v_pk_add_f32 v[158:159], v[158:159], 1.0 op_sel_hi:[1,0]
	v_pk_mul_f32 v[206:207], v[146:147], v[152:153]
	v_lshlrev_b64 v[146:147], 12, v[198:199]
	v_lshl_add_u64 v[146:147], v[220:221], 0, v[146:147]
	global_load_dwordx4 v[226:229], v[146:147], off offset:16
	global_load_dwordx4 v[244:247], v[146:147], off
	global_load_dwordx4 v[162:165], v[146:147], off offset:528
	global_load_dwordx4 v[166:169], v[146:147], off offset:512
	v_pk_mul_f32 v[202:203], v[150:151], v[158:159]
	v_pk_add_f32 v[150:151], v[156:157], 1.0 op_sel_hi:[1,0]
	v_lshlrev_b64 v[146:147], 12, v[218:219]
	v_pk_mul_f32 v[204:205], v[148:149], v[150:151]
	v_lshl_add_u64 v[150:151], v[220:221], 0, v[146:147]
	global_load_dwordx4 v[154:157], v[150:151], off offset:16
	global_load_dwordx4 v[158:161], v[150:151], off
	global_load_dwordx4 v[146:149], v[150:151], off offset:528
	s_nop 0
	global_load_dwordx4 v[150:153], v[150:151], off offset:512
	s_waitcnt vmcnt(0)
	v_pk_fma_f32 v[144:145], v[144:145], v[76:77], v[228:229]
	v_pk_fma_f32 v[246:247], v[140:141], v[80:81], v[246:247]
	v_pk_fma_f32 v[244:245], v[138:139], v[78:79], v[244:245]
	v_mul_f32_e32 v141, v247, v247
	v_mul_f32_e32 v140, v245, v245
	v_pk_fma_f32 v[142:143], v[142:143], v[74:75], v[226:227]
	v_fmac_f32_e32 v140, v244, v244
	v_fmac_f32_e32 v141, v246, v246
	v_add_f32_e32 v140, v140, v141
	v_mul_f32_e32 v141, v143, v143
	v_mul_f32_e32 v226, v145, v145
	v_fmac_f32_e32 v141, v142, v142
	v_fmac_f32_e32 v226, v144, v144
	v_lshl_add_u64 v[138:139], v[248:249], 2, s[44:45]
	v_add_f32_e32 v141, v141, v226
	global_store_dwordx4 v[138:139], v[244:247], off
	global_store_dwordx4 v[138:139], v[142:145], off offset:16
	v_add_f32_e32 v228, v140, v141
	v_pk_mul_f32 v[140:141], v[210:211], v[244:245]
	v_pk_mul_f32 v[144:145], v[212:213], v[144:145]
	v_pk_mul_f32 v[142:143], v[214:215], v[142:143]
	v_pk_mul_f32 v[226:227], v[208:209], v[246:247]
	v_cvt_pk_bf16_f32 v140, v140, v141
	v_pk_fma_f32 v[136:137], v[136:137], v[72:73], v[168:169]
	v_cvt_pk_bf16_f32 v141, v226, v227
	v_cvt_pk_bf16_f32 v142, v142, v143
	v_cvt_pk_bf16_f32 v143, v144, v145
	v_lshl_add_u64 v[144:145], v[248:249], 1, s[34:35]
	v_pk_fma_f32 v[134:135], v[134:135], v[70:71], v[166:167]
	global_store_dwordx4 v[144:145], v[140:143], off
	v_pk_fma_f32 v[132:133], v[132:133], v[68:69], v[164:165]
	v_pk_fma_f32 v[130:131], v[130:131], v[66:67], v[162:163]
	global_store_dwordx4 v[138:139], v[134:137], off offset:512
	global_store_dwordx4 v[138:139], v[130:133], off offset:528
	v_mul_f32_e32 v138, v135, v135
	v_mul_f32_e32 v139, v137, v137
	v_fmac_f32_e32 v138, v134, v134
	v_fmac_f32_e32 v139, v136, v136
	v_add_f32_e32 v138, v138, v139
	v_mul_f32_e32 v139, v131, v131
	v_mul_f32_e32 v140, v133, v133
	v_fmac_f32_e32 v139, v130, v130
	v_fmac_f32_e32 v140, v132, v132
	v_add_f32_e32 v139, v139, v140
	v_add_f32_e32 v138, v138, v139
	v_pk_mul_f32 v[134:135], v[202:203], v[134:135]
	v_pk_fma_f32 v[128:129], v[128:129], v[80:81], v[160:161]
	v_pk_fma_f32 v[126:127], v[126:127], v[78:79], v[158:159]
	v_add_f32_e32 v142, v228, v138
	v_pk_mul_f32 v[136:137], v[200:201], v[136:137]
	v_pk_mul_f32 v[138:139], v[204:205], v[132:133]
	v_pk_mul_f32 v[132:133], v[206:207], v[130:131]
	v_cvt_pk_bf16_f32 v130, v134, v135
	v_cvt_pk_bf16_f32 v131, v136, v137
	v_mul_f32_e32 v134, v127, v127
	v_mul_f32_e32 v135, v129, v129
	v_cvt_pk_bf16_f32 v132, v132, v133
	v_cvt_pk_bf16_f32 v133, v138, v139
	global_store_dwordx4 v[144:145], v[130:133], off offset:256
	v_pk_fma_f32 v[124:125], v[124:125], v[76:77], v[156:157]
	v_pk_fma_f32 v[122:123], v[122:123], v[74:75], v[154:155]
	v_lshlrev_b64 v[130:131], 10, v[218:219]
	v_fmac_f32_e32 v134, v126, v126
	v_fmac_f32_e32 v135, v128, v128
	v_lshl_add_u64 v[130:131], v[130:131], 0, v[216:217]
	v_add_f32_e32 v134, v134, v135
	v_mul_f32_e32 v135, v123, v123
	v_mul_f32_e32 v136, v125, v125
	v_lshl_add_u64 v[132:133], v[130:131], 2, s[44:45]
	v_fmac_f32_e32 v135, v122, v122
	v_fmac_f32_e32 v136, v124, v124
	global_store_dwordx4 v[132:133], v[126:129], off
	global_store_dwordx4 v[132:133], v[122:125], off offset:16
	v_add_f32_e32 v135, v135, v136
	v_pk_mul_f32 v[126:127], v[210:211], v[126:127]
	v_add_f32_e32 v136, v134, v135
	v_pk_mul_f32 v[128:129], v[208:209], v[128:129]
	v_pk_mul_f32 v[134:135], v[212:213], v[124:125]
	v_pk_mul_f32 v[124:125], v[214:215], v[122:123]
	v_cvt_pk_bf16_f32 v122, v126, v127
	v_cvt_pk_bf16_f32 v123, v128, v129
	v_lshl_add_u64 v[126:127], v[130:131], 1, s[34:35]
	v_pk_fma_f32 v[120:121], v[120:121], v[72:73], v[152:153]
	v_pk_fma_f32 v[118:119], v[118:119], v[70:71], v[150:151]
	v_cvt_pk_bf16_f32 v124, v124, v125
	v_cvt_pk_bf16_f32 v125, v134, v135
	global_store_dwordx4 v[126:127], v[122:125], off
	v_pk_fma_f32 v[116:117], v[116:117], v[68:69], v[148:149]
	v_pk_fma_f32 v[114:115], v[114:115], v[66:67], v[146:147]
	v_mul_f32_e32 v122, v119, v119
	v_mul_f32_e32 v123, v121, v121
	v_fmac_f32_e32 v122, v118, v118
	v_fmac_f32_e32 v123, v120, v120
	v_add_f32_e32 v122, v122, v123
	v_mul_f32_e32 v123, v115, v115
	v_mul_f32_e32 v124, v117, v117
	v_fmac_f32_e32 v123, v114, v114
	v_fmac_f32_e32 v124, v116, v116
	v_add_f32_e32 v123, v123, v124
	v_add_f32_e32 v122, v122, v123
	v_or_b32_e32 v138, 32, v198
	global_store_dwordx4 v[132:133], v[118:121], off offset:512
	global_store_dwordx4 v[132:133], v[114:117], off offset:528
	v_add_f32_e32 v143, v136, v122
	v_pk_mul_f32 v[120:121], v[200:201], v[120:121]
	v_pk_mul_f32 v[118:119], v[202:203], v[118:119]
	v_pk_mul_f32 v[122:123], v[204:205], v[116:117]
	v_pk_mul_f32 v[116:117], v[206:207], v[114:115]
	v_cvt_pk_bf16_f32 v114, v118, v119
	v_cvt_pk_bf16_f32 v115, v120, v121
	v_ashrrev_i32_e32 v139, 31, v138
	v_cvt_pk_bf16_f32 v116, v116, v117
	v_cvt_pk_bf16_f32 v117, v122, v123
	global_store_dwordx4 v[126:127], v[114:117], off offset:256
	v_or_b32_e32 v140, 48, v198
	v_ashrrev_i32_e32 v141, 31, v140
	v_lshlrev_b64 v[114:115], 12, v[138:139]
	v_lshl_add_u64 v[114:115], v[220:221], 0, v[114:115]
	global_load_dwordx4 v[144:147], v[114:115], off offset:16
	global_load_dwordx4 v[148:151], v[114:115], off
	global_load_dwordx4 v[130:133], v[114:115], off offset:528
	global_load_dwordx4 v[134:137], v[114:115], off offset:512
	v_lshlrev_b64 v[114:115], 12, v[140:141]
	v_lshl_add_u64 v[118:119], v[220:221], 0, v[114:115]
	global_load_dwordx4 v[122:125], v[118:119], off offset:16
	global_load_dwordx4 v[126:129], v[118:119], off
	global_load_dwordx4 v[114:117], v[118:119], off offset:528
	s_nop 0
	global_load_dwordx4 v[118:121], v[118:119], off offset:512
	v_lshlrev_b64 v[152:153], 10, v[138:139]
	v_lshl_add_u64 v[152:153], v[152:153], 0, v[216:217]
	s_waitcnt vmcnt(0)
	v_add_u32_e32 v252, 0x80, v198
	v_ashrrev_i32_e32 v253, 31, v252
	v_lshlrev_b64 v[252:253], 12, v[252:253]
	v_lshl_add_u64 v[252:253], v[220:221], 0, v[252:253]
	global_load_dwordx4 v[154:157], v[252:253], off offset:16
	global_load_dwordx4 v[158:161], v[252:253], off
	global_load_dwordx4 v[162:165], v[252:253], off offset:528
	global_load_dwordx4 v[166:169], v[252:253], off offset:512
	v_add_u32_e32 v252, 0x90, v198
	v_ashrrev_i32_e32 v253, 31, v252
	v_lshlrev_b64 v[252:253], 12, v[252:253]
	v_lshl_add_u64 v[252:253], v[220:221], 0, v[252:253]
	global_load_dwordx4 v[226:229], v[252:253], off offset:16
	global_load_dwordx4 v[244:247], v[252:253], off
	global_load_dwordx4 v[248:251], v[252:253], off offset:528
	v_pk_fma_f32 v[108:109], v[108:109], v[76:77], v[146:147]
	v_pk_fma_f32 v[112:113], v[112:113], v[80:81], v[150:151]
	v_pk_fma_f32 v[110:111], v[110:111], v[78:79], v[148:149]
	v_mul_f32_e32 v147, v113, v113
	v_mul_f32_e32 v146, v111, v111
	v_pk_fma_f32 v[106:107], v[106:107], v[74:75], v[144:145]
	v_fmac_f32_e32 v146, v110, v110
	v_fmac_f32_e32 v147, v112, v112
	v_add_f32_e32 v146, v146, v147
	v_mul_f32_e32 v147, v107, v107
	v_mul_f32_e32 v148, v109, v109
	v_lshl_add_u64 v[144:145], v[152:153], 2, s[44:45]
	v_fmac_f32_e32 v147, v106, v106
	v_fmac_f32_e32 v148, v108, v108
	global_store_dwordx4 v[144:145], v[110:113], off
	global_store_dwordx4 v[144:145], v[106:109], off offset:16
	v_add_f32_e32 v147, v147, v148
	v_pk_mul_f32 v[110:111], v[210:211], v[110:111]
	v_add_f32_e32 v148, v146, v147
	v_pk_mul_f32 v[112:113], v[208:209], v[112:113]
	v_pk_mul_f32 v[146:147], v[212:213], v[108:109]
	v_pk_mul_f32 v[108:109], v[214:215], v[106:107]
	v_cvt_pk_bf16_f32 v106, v110, v111
	v_cvt_pk_bf16_f32 v107, v112, v113
	v_lshl_add_u64 v[110:111], v[152:153], 1, s[34:35]
	v_pk_fma_f32 v[104:105], v[104:105], v[72:73], v[136:137]
	v_pk_fma_f32 v[102:103], v[102:103], v[70:71], v[134:135]
	global_load_dwordx4 v[134:137], v[252:253], off offset:512
	v_cvt_pk_bf16_f32 v108, v108, v109
	v_cvt_pk_bf16_f32 v109, v146, v147
	global_store_dwordx4 v[110:111], v[106:109], off
	v_pk_fma_f32 v[100:101], v[100:101], v[68:69], v[132:133]
	v_pk_fma_f32 v[98:99], v[98:99], v[66:67], v[130:131]
	v_mul_f32_e32 v106, v103, v103
	v_mul_f32_e32 v107, v105, v105
	v_fmac_f32_e32 v106, v102, v102
	v_fmac_f32_e32 v107, v104, v104
	v_add_f32_e32 v106, v106, v107
	v_mul_f32_e32 v107, v99, v99
	v_mul_f32_e32 v108, v101, v101
	v_fmac_f32_e32 v107, v98, v98
	v_fmac_f32_e32 v108, v100, v100
	v_add_f32_e32 v107, v107, v108
	global_store_dwordx4 v[144:145], v[102:105], off offset:512
	global_store_dwordx4 v[144:145], v[98:101], off offset:528
	v_add_f32_e32 v106, v106, v107
	v_pk_mul_f32 v[102:103], v[202:203], v[102:103]
	v_pk_fma_f32 v[96:97], v[96:97], v[80:81], v[128:129]
	v_pk_fma_f32 v[94:95], v[94:95], v[78:79], v[126:127]
	v_add_f32_e32 v130, v148, v106
	v_pk_mul_f32 v[104:105], v[200:201], v[104:105]
	v_pk_mul_f32 v[106:107], v[204:205], v[100:101]
	v_pk_mul_f32 v[100:101], v[206:207], v[98:99]
	v_cvt_pk_bf16_f32 v98, v102, v103
	v_cvt_pk_bf16_f32 v99, v104, v105
	v_mul_f32_e32 v102, v95, v95
	v_mul_f32_e32 v103, v97, v97
	v_cvt_pk_bf16_f32 v100, v100, v101
	v_cvt_pk_bf16_f32 v101, v106, v107
	global_store_dwordx4 v[110:111], v[98:101], off offset:256
	v_pk_fma_f32 v[92:93], v[92:93], v[76:77], v[124:125]
	v_pk_fma_f32 v[90:91], v[90:91], v[74:75], v[122:123]
	v_lshlrev_b64 v[98:99], 10, v[140:141]
	v_fmac_f32_e32 v102, v94, v94
	v_fmac_f32_e32 v103, v96, v96
	v_lshl_add_u64 v[98:99], v[98:99], 0, v[216:217]
	v_add_f32_e32 v102, v102, v103
	v_mul_f32_e32 v103, v91, v91
	v_mul_f32_e32 v104, v93, v93
	v_lshl_add_u64 v[100:101], v[98:99], 2, s[44:45]
	v_fmac_f32_e32 v103, v90, v90
	v_fmac_f32_e32 v104, v92, v92
	global_store_dwordx4 v[100:101], v[94:97], off
	global_store_dwordx4 v[100:101], v[90:93], off offset:16
	v_add_f32_e32 v103, v103, v104
	v_pk_mul_f32 v[94:95], v[210:211], v[94:95]
	v_add_f32_e32 v104, v102, v103
	v_pk_mul_f32 v[96:97], v[208:209], v[96:97]
	v_pk_mul_f32 v[102:103], v[212:213], v[92:93]
	v_pk_mul_f32 v[92:93], v[214:215], v[90:91]
	v_cvt_pk_bf16_f32 v90, v94, v95
	v_cvt_pk_bf16_f32 v91, v96, v97
	v_lshl_add_u64 v[94:95], v[98:99], 1, s[34:35]
	v_pk_fma_f32 v[88:89], v[88:89], v[72:73], v[120:121]
	v_pk_fma_f32 v[86:87], v[86:87], v[70:71], v[118:119]
	v_cvt_pk_bf16_f32 v92, v92, v93
	v_cvt_pk_bf16_f32 v93, v102, v103
	global_store_dwordx4 v[94:95], v[90:93], off
	v_pk_fma_f32 v[84:85], v[84:85], v[68:69], v[116:117]
	v_pk_fma_f32 v[82:83], v[82:83], v[66:67], v[114:115]
	v_mul_f32_e32 v90, v87, v87
	v_mul_f32_e32 v91, v89, v89
	v_fmac_f32_e32 v90, v86, v86
	v_fmac_f32_e32 v91, v88, v88
	v_add_f32_e32 v90, v90, v91
	v_mul_f32_e32 v91, v83, v83
	v_mul_f32_e32 v92, v85, v85
	v_fmac_f32_e32 v91, v82, v82
	v_fmac_f32_e32 v92, v84, v84
	v_add_f32_e32 v91, v91, v92
	v_add_f32_e32 v90, v90, v91
	v_add_u32_e32 v114, 0x80, v198
	global_store_dwordx4 v[100:101], v[86:89], off offset:512
	global_store_dwordx4 v[100:101], v[82:85], off offset:528
	v_add_f32_e32 v118, v104, v90
	v_pk_mul_f32 v[88:89], v[200:201], v[88:89]
	v_pk_mul_f32 v[86:87], v[202:203], v[86:87]
	v_pk_mul_f32 v[90:91], v[204:205], v[84:85]
	v_pk_mul_f32 v[84:85], v[206:207], v[82:83]
	v_cvt_pk_bf16_f32 v82, v86, v87
	v_cvt_pk_bf16_f32 v83, v88, v89
	v_ashrrev_i32_e32 v115, 31, v114
	v_cvt_pk_bf16_f32 v84, v84, v85
	v_cvt_pk_bf16_f32 v85, v90, v91
	global_store_dwordx4 v[94:95], v[82:85], off offset:256
	v_add_u32_e32 v116, 0x90, v198
	v_ashrrev_i32_e32 v117, 31, v116
	v_lshlrev_b64 v[82:83], 12, v[114:115]
	v_lshl_add_u64 v[82:83], v[220:221], 0, v[82:83]
	v_lshlrev_b64 v[82:83], 12, v[116:117]
	v_lshl_add_u64 v[86:87], v[220:221], 0, v[82:83]
	v_lshlrev_b64 v[120:121], 10, v[114:115]
	v_lshl_add_u64 v[120:121], v[120:121], 0, v[216:217]
	s_waitcnt vmcnt(10)
	v_mov_b64_e32 v[106:107], v[154:155]
	v_mov_b64_e32 v[108:109], v[156:157]
	v_mov_b64_e32 v[110:111], v[158:159]
	v_mov_b64_e32 v[112:113], v[160:161]
	v_mov_b64_e32 v[98:99], v[162:163]
	v_mov_b64_e32 v[100:101], v[164:165]
	v_mov_b64_e32 v[102:103], v[166:167]
	v_mov_b64_e32 v[104:105], v[168:169]
	v_mov_b64_e32 v[90:91], v[226:227]
	v_mov_b64_e32 v[92:93], v[228:229]
	v_mov_b64_e32 v[94:95], v[244:245]
	v_mov_b64_e32 v[96:97], v[246:247]
	v_mov_b64_e32 v[82:83], v[248:249]
	v_mov_b64_e32 v[84:85], v[250:251]
	v_mov_b64_e32 v[86:87], v[134:135]
	v_mov_b64_e32 v[88:89], v[136:137]
	v_add_u32_e32 v252, 0xa0, v198
	v_ashrrev_i32_e32 v253, 31, v252
	v_lshlrev_b64 v[252:253], 12, v[252:253]
	v_lshl_add_u64 v[252:253], v[220:221], 0, v[252:253]
	global_load_dwordx4 v[122:125], v[252:253], off offset:16
	global_load_dwordx4 v[126:129], v[252:253], off
	global_load_dwordx4 v[144:147], v[252:253], off offset:528
	global_load_dwordx4 v[148:151], v[252:253], off offset:512
	v_add_u32_e32 v252, 0xb0, v198
	v_ashrrev_i32_e32 v253, 31, v252
	v_lshlrev_b64 v[252:253], 12, v[252:253]
	v_lshl_add_u64 v[252:253], v[220:221], 0, v[252:253]
	global_load_dwordx4 v[152:155], v[252:253], off offset:16
	global_load_dwordx4 v[156:159], v[252:253], off
	global_load_dwordx4 v[160:163], v[252:253], off offset:528
	global_load_dwordx4 v[164:167], v[252:253], off offset:512
	v_pk_fma_f32 v[60:61], v[60:61], v[76:77], v[108:109]
	v_pk_fma_f32 v[64:65], v[64:65], v[80:81], v[112:113]
	v_pk_fma_f32 v[62:63], v[62:63], v[78:79], v[110:111]
	v_mul_f32_e32 v109, v65, v65
	v_mul_f32_e32 v108, v63, v63
	v_pk_fma_f32 v[58:59], v[58:59], v[74:75], v[106:107]
	v_fmac_f32_e32 v108, v62, v62
	v_fmac_f32_e32 v109, v64, v64
	v_add_f32_e32 v108, v108, v109
	v_mul_f32_e32 v109, v59, v59
	v_mul_f32_e32 v110, v61, v61
	v_lshl_add_u64 v[106:107], v[120:121], 2, s[44:45]
	v_fmac_f32_e32 v109, v58, v58
	v_fmac_f32_e32 v110, v60, v60
	global_store_dwordx4 v[106:107], v[62:65], off
	global_store_dwordx4 v[106:107], v[58:61], off offset:16
	v_add_f32_e32 v109, v109, v110
	v_pk_mul_f32 v[62:63], v[210:211], v[62:63]
	v_add_f32_e32 v110, v108, v109
	v_pk_mul_f32 v[64:65], v[208:209], v[64:65]
	v_pk_mul_f32 v[108:109], v[212:213], v[60:61]
	v_pk_mul_f32 v[60:61], v[214:215], v[58:59]
	v_cvt_pk_bf16_f32 v58, v62, v63
	v_cvt_pk_bf16_f32 v59, v64, v65
	v_lshl_add_u64 v[62:63], v[120:121], 1, s[34:35]
	v_pk_fma_f32 v[56:57], v[56:57], v[72:73], v[104:105]
	v_pk_fma_f32 v[54:55], v[54:55], v[70:71], v[102:103]
	v_cvt_pk_bf16_f32 v60, v60, v61
	v_cvt_pk_bf16_f32 v61, v108, v109
	global_store_dwordx4 v[62:63], v[58:61], off
	v_pk_fma_f32 v[48:49], v[48:49], v[80:81], v[96:97]
	v_pk_fma_f32 v[46:47], v[46:47], v[78:79], v[94:95]
	v_pk_fma_f32 v[58:59], v[50:51], v[66:67], v[98:99]
	v_mul_f32_e32 v50, v55, v55
	v_mul_f32_e32 v51, v57, v57
	v_pk_fma_f32 v[60:61], v[52:53], v[68:69], v[100:101]
	v_fmac_f32_e32 v50, v54, v54
	v_fmac_f32_e32 v51, v56, v56
	v_add_f32_e32 v50, v50, v51
	v_mul_f32_e32 v51, v59, v59
	v_mul_f32_e32 v52, v61, v61
	v_fmac_f32_e32 v51, v58, v58
	v_fmac_f32_e32 v52, v60, v60
	global_store_dwordx4 v[106:107], v[54:57], off offset:512
	global_store_dwordx4 v[106:107], v[58:61], off offset:528
	v_add_f32_e32 v51, v51, v52
	v_pk_mul_f32 v[56:57], v[200:201], v[56:57]
	v_pk_mul_f32 v[52:53], v[202:203], v[54:55]
	v_add_f32_e32 v50, v50, v51
	v_pk_mul_f32 v[54:55], v[206:207], v[58:59]
	v_cvt_pk_bf16_f32 v52, v52, v53
	v_cvt_pk_bf16_f32 v53, v56, v57
	v_mul_f32_e32 v51, v47, v47
	v_mul_f32_e32 v56, v49, v49
	v_pk_mul_f32 v[60:61], v[204:205], v[60:61]
	v_cvt_pk_bf16_f32 v54, v54, v55
	v_pk_fma_f32 v[44:45], v[44:45], v[76:77], v[92:93]
	v_cvt_pk_bf16_f32 v55, v60, v61
	global_store_dwordx4 v[62:63], v[52:55], off offset:256
	v_pk_fma_f32 v[42:43], v[42:43], v[74:75], v[90:91]
	v_fmac_f32_e32 v51, v46, v46
	v_lshlrev_b64 v[52:53], 10, v[116:117]
	v_fmac_f32_e32 v56, v48, v48
	v_lshl_add_u64 v[52:53], v[52:53], 0, v[216:217]
	v_add_f32_e32 v51, v51, v56
	v_mul_f32_e32 v56, v43, v43
	v_mul_f32_e32 v57, v45, v45
	v_lshl_add_u64 v[54:55], v[52:53], 2, s[44:45]
	v_fmac_f32_e32 v56, v42, v42
	v_fmac_f32_e32 v57, v44, v44
	global_store_dwordx4 v[54:55], v[46:49], off
	global_store_dwordx4 v[54:55], v[42:45], off offset:16
	v_add_f32_e32 v56, v56, v57
	v_pk_mul_f32 v[46:47], v[210:211], v[46:47]
	v_add_f32_e32 v51, v51, v56
	v_pk_mul_f32 v[48:49], v[208:209], v[48:49]
	v_pk_mul_f32 v[56:57], v[212:213], v[44:45]
	v_pk_mul_f32 v[44:45], v[214:215], v[42:43]
	v_cvt_pk_bf16_f32 v42, v46, v47
	v_cvt_pk_bf16_f32 v43, v48, v49
	v_lshl_add_u64 v[46:47], v[52:53], 1, s[34:35]
	v_pk_fma_f32 v[40:41], v[40:41], v[72:73], v[88:89]
	v_pk_fma_f32 v[38:39], v[38:39], v[70:71], v[86:87]
	v_cvt_pk_bf16_f32 v44, v44, v45
	v_cvt_pk_bf16_f32 v45, v56, v57
	global_store_dwordx4 v[46:47], v[42:45], off
	v_pk_fma_f32 v[36:37], v[36:37], v[68:69], v[84:85]
	v_pk_fma_f32 v[34:35], v[34:35], v[66:67], v[82:83]
	v_mul_f32_e32 v42, v39, v39
	v_mul_f32_e32 v43, v41, v41
	v_fmac_f32_e32 v42, v38, v38
	v_fmac_f32_e32 v43, v40, v40
	v_add_f32_e32 v42, v42, v43
	v_mul_f32_e32 v43, v35, v35
	v_mul_f32_e32 v44, v37, v37
	v_fmac_f32_e32 v43, v34, v34
	v_fmac_f32_e32 v44, v36, v36
	v_add_f32_e32 v43, v43, v44
	v_add_f32_e32 v42, v42, v43
	global_store_dwordx4 v[54:55], v[38:41], off offset:512
	global_store_dwordx4 v[54:55], v[34:37], off offset:528
	v_add_f32_e32 v51, v51, v42
	v_pk_mul_f32 v[42:43], v[204:205], v[36:37]
	v_pk_mul_f32 v[36:37], v[206:207], v[34:35]
	v_pk_mul_f32 v[40:41], v[200:201], v[40:41]
	v_pk_mul_f32 v[38:39], v[202:203], v[38:39]
	v_add_f32_e32 v50, v110, v50
	v_cvt_pk_bf16_f32 v34, v38, v39
	v_cvt_pk_bf16_f32 v35, v40, v41
	v_cvt_pk_bf16_f32 v36, v36, v37
	v_cvt_pk_bf16_f32 v37, v42, v43
	global_store_dwordx4 v[46:47], v[34:37], off offset:256
	v_add_u32_e32 v46, 0xa0, v198
	v_ashrrev_i32_e32 v47, 31, v46
	v_lshlrev_b64 v[34:35], 12, v[46:47]
	v_lshl_add_u64 v[48:49], v[220:221], 0, v[34:35]
	v_add_u32_e32 v48, 0xb0, v198
	v_ashrrev_i32_e32 v49, 31, v48
	v_lshlrev_b64 v[56:57], 12, v[48:49]
	v_lshl_add_u64 v[64:65], v[220:221], 0, v[56:57]
	v_lshlrev_b64 v[64:65], 10, v[46:47]
	v_lshl_add_u64 v[64:65], v[64:65], 0, v[216:217]
	s_waitcnt vmcnt(12)
	v_mov_b64_e32 v[38:39], v[122:123]
	v_mov_b64_e32 v[40:41], v[124:125]
	v_mov_b64_e32 v[42:43], v[126:127]
	v_mov_b64_e32 v[44:45], v[128:129]
	v_mov_b64_e32 v[34:35], v[144:145]
	v_mov_b64_e32 v[36:37], v[146:147]
	v_mov_b64_e32 v[52:53], v[148:149]
	v_mov_b64_e32 v[54:55], v[150:151]
	v_mov_b64_e32 v[56:57], v[152:153]
	v_mov_b64_e32 v[58:59], v[154:155]
	v_mov_b64_e32 v[60:61], v[156:157]
	v_mov_b64_e32 v[62:63], v[158:159]
	v_mov_b64_e32 v[82:83], v[160:161]
	v_mov_b64_e32 v[84:85], v[162:163]
	v_mov_b64_e32 v[86:87], v[164:165]
	v_mov_b64_e32 v[88:89], v[166:167]
	v_pk_fma_f32 v[28:29], v[28:29], v[76:77], v[40:41]
	v_pk_fma_f32 v[32:33], v[32:33], v[80:81], v[44:45]
	v_pk_fma_f32 v[30:31], v[30:31], v[78:79], v[42:43]
	v_mul_f32_e32 v41, v33, v33
	v_mul_f32_e32 v40, v31, v31
	v_pk_fma_f32 v[26:27], v[26:27], v[74:75], v[38:39]
	v_fmac_f32_e32 v40, v30, v30
	v_fmac_f32_e32 v41, v32, v32
	v_add_f32_e32 v40, v40, v41
	v_mul_f32_e32 v41, v27, v27
	v_mul_f32_e32 v42, v29, v29
	v_lshl_add_u64 v[38:39], v[64:65], 2, s[44:45]
	v_fmac_f32_e32 v41, v26, v26
	v_fmac_f32_e32 v42, v28, v28
	global_store_dwordx4 v[38:39], v[30:33], off
	global_store_dwordx4 v[38:39], v[26:29], off offset:16
	v_add_f32_e32 v41, v41, v42
	v_pk_mul_f32 v[30:31], v[210:211], v[30:31]
	v_add_f32_e32 v42, v40, v41
	v_pk_mul_f32 v[32:33], v[208:209], v[32:33]
	v_pk_mul_f32 v[40:41], v[212:213], v[28:29]
	v_pk_mul_f32 v[28:29], v[214:215], v[26:27]
	v_cvt_pk_bf16_f32 v26, v30, v31
	v_cvt_pk_bf16_f32 v27, v32, v33
	v_lshl_add_u64 v[30:31], v[64:65], 1, s[34:35]
	v_pk_fma_f32 v[24:25], v[24:25], v[72:73], v[54:55]
	v_pk_fma_f32 v[22:23], v[22:23], v[70:71], v[52:53]
	v_cvt_pk_bf16_f32 v28, v28, v29
	v_cvt_pk_bf16_f32 v29, v40, v41
	global_store_dwordx4 v[30:31], v[26:29], off
	v_pk_fma_f32 v[20:21], v[20:21], v[68:69], v[36:37]
	v_pk_fma_f32 v[18:19], v[18:19], v[66:67], v[34:35]
	v_mul_f32_e32 v26, v23, v23
	v_mul_f32_e32 v27, v25, v25
	v_fmac_f32_e32 v26, v22, v22
	v_fmac_f32_e32 v27, v24, v24
	v_add_f32_e32 v26, v26, v27
	v_mul_f32_e32 v27, v19, v19
	v_mul_f32_e32 v28, v21, v21
	v_fmac_f32_e32 v27, v18, v18
	v_fmac_f32_e32 v28, v20, v20
	v_add_f32_e32 v27, v27, v28
	global_store_dwordx4 v[38:39], v[22:25], off offset:512
	global_store_dwordx4 v[38:39], v[18:21], off offset:528
	v_add_f32_e32 v26, v26, v27
	v_pk_mul_f32 v[22:23], v[202:203], v[22:23]
	v_pk_fma_f32 v[16:17], v[16:17], v[80:81], v[62:63]
	v_pk_fma_f32 v[14:15], v[14:15], v[78:79], v[60:61]
	v_add_f32_e32 v28, v42, v26
	v_pk_mul_f32 v[24:25], v[200:201], v[24:25]
	v_pk_mul_f32 v[26:27], v[204:205], v[20:21]
	v_pk_mul_f32 v[20:21], v[206:207], v[18:19]
	v_cvt_pk_bf16_f32 v18, v22, v23
	v_cvt_pk_bf16_f32 v19, v24, v25
	v_mul_f32_e32 v22, v15, v15
	v_mul_f32_e32 v23, v17, v17
	v_cvt_pk_bf16_f32 v20, v20, v21
	v_cvt_pk_bf16_f32 v21, v26, v27
	global_store_dwordx4 v[30:31], v[18:21], off offset:256
	v_pk_fma_f32 v[12:13], v[12:13], v[76:77], v[58:59]
	v_pk_fma_f32 v[10:11], v[10:11], v[74:75], v[56:57]
	v_lshlrev_b64 v[18:19], 10, v[48:49]
	v_fmac_f32_e32 v22, v14, v14
	v_fmac_f32_e32 v23, v16, v16
	v_lshl_add_u64 v[18:19], v[18:19], 0, v[216:217]
	v_add_f32_e32 v22, v22, v23
	v_mul_f32_e32 v23, v11, v11
	v_mul_f32_e32 v24, v13, v13
	v_lshl_add_u64 v[20:21], v[18:19], 2, s[44:45]
	v_fmac_f32_e32 v23, v10, v10
	v_fmac_f32_e32 v24, v12, v12
	global_store_dwordx4 v[20:21], v[14:17], off
	global_store_dwordx4 v[20:21], v[10:13], off offset:16
	v_add_f32_e32 v23, v23, v24
	v_pk_mul_f32 v[14:15], v[210:211], v[14:15]
	v_add_f32_e32 v24, v22, v23
	v_pk_mul_f32 v[16:17], v[208:209], v[16:17]
	v_pk_mul_f32 v[22:23], v[212:213], v[12:13]
	v_pk_mul_f32 v[12:13], v[214:215], v[10:11]
	v_cvt_pk_bf16_f32 v10, v14, v15
	v_cvt_pk_bf16_f32 v11, v16, v17
	v_lshl_add_u64 v[14:15], v[18:19], 1, s[34:35]
	v_pk_fma_f32 v[8:9], v[8:9], v[72:73], v[88:89]
	v_pk_fma_f32 v[6:7], v[6:7], v[70:71], v[86:87]
	v_cvt_pk_bf16_f32 v12, v12, v13
	v_cvt_pk_bf16_f32 v13, v22, v23
	global_store_dwordx4 v[14:15], v[10:13], off
	v_pk_fma_f32 v[4:5], v[4:5], v[68:69], v[84:85]
	v_pk_fma_f32 v[2:3], v[2:3], v[66:67], v[82:83]
	v_mul_f32_e32 v10, v7, v7
	v_mul_f32_e32 v11, v9, v9
	v_fmac_f32_e32 v10, v6, v6
	v_fmac_f32_e32 v11, v8, v8
	v_add_f32_e32 v10, v10, v11
	v_mul_f32_e32 v11, v3, v3
	v_mul_f32_e32 v12, v5, v5
	v_fmac_f32_e32 v11, v2, v2
	v_fmac_f32_e32 v12, v4, v4
	v_add_f32_e32 v11, v11, v12
	v_add_f32_e32 v10, v10, v11
	global_store_dwordx4 v[20:21], v[6:9], off offset:512
	global_store_dwordx4 v[20:21], v[2:5], off offset:528
	v_add_f32_e32 v12, v24, v10
	v_pk_mul_f32 v[8:9], v[200:201], v[8:9]
	v_pk_mul_f32 v[10:11], v[204:205], v[4:5]
	v_pk_mul_f32 v[4:5], v[206:207], v[2:3]
	v_pk_mul_f32 v[6:7], v[202:203], v[6:7]
	s_nop 0
	v_cvt_pk_bf16_f32 v2, v6, v7
	v_cvt_pk_bf16_f32 v3, v8, v9
	v_cvt_pk_bf16_f32 v4, v4, v5
	v_cvt_pk_bf16_f32 v5, v10, v11
	v_lshlrev_b32_e32 v9, 6, v224
	v_lshlrev_b32_e32 v10, 2, v225
	v_bitop3_b32 v11, v9, 64, v10 bitop3:0x36
	global_store_dwordx4 v[14:15], v[2:5], off offset:256
	ds_bpermute_b32 v2, v11, v142
	ds_bpermute_b32 v3, v11, v143
	ds_bpermute_b32 v4, v11, v130
	ds_bpermute_b32 v5, v11, v118
	ds_bpermute_b32 v6, v11, v50
	ds_bpermute_b32 v7, v11, v51
	ds_bpermute_b32 v8, v11, v28
	ds_bpermute_b32 v11, v11, v12
	s_waitcnt lgkmcnt(0)
	v_add_f32_e32 v2, v142, v2
	v_add_f32_e32 v3, v143, v3
	v_add_f32_e32 v4, v130, v4
	v_add_f32_e32 v5, v118, v5
	v_add_f32_e32 v6, v50, v6
	v_add_f32_e32 v7, v51, v7
	v_add_f32_e32 v8, v28, v8
	v_add_f32_e32 v12, v12, v11
	v_bitop3_b32 v17, v9, s90, v10 bitop3:0x36
	ds_bpermute_b32 v9, v17, v2
	ds_bpermute_b32 v10, v17, v3
	ds_bpermute_b32 v11, v17, v4
	ds_bpermute_b32 v13, v17, v5
	ds_bpermute_b32 v14, v17, v6
	ds_bpermute_b32 v15, v17, v7
	ds_bpermute_b32 v16, v17, v8
	ds_bpermute_b32 v17, v17, v12
	s_and_saveexec_b64 s[0:1], vcc
	s_cbranch_execz .LBB0_1321
	s_lshl_b32 s2, s88, 2
	s_ashr_i32 s3, s2, 31
	s_lshl_b64 s[2:3], s[2:3], 2
	s_add_u32 s2, s71, s2
	s_addc_u32 s3, s72, s3
	v_lshlrev_b32_e32 v0, 2, v0
	s_waitcnt lgkmcnt(4)
	v_add_f32_e32 v13, v5, v13
	v_add_f32_e32 v11, v4, v11
	v_add_f32_e32 v10, v3, v10
	v_add_f32_e32 v9, v2, v9
	v_lshl_add_u64 v[2:3], s[2:3], 0, v[0:1]
	v_lshlrev_b64 v[4:5], 6, v[198:199]
	v_lshl_add_u64 v[4:5], v[2:3], 0, v[4:5]
	global_store_dword v[4:5], v9, off
	v_lshlrev_b64 v[4:5], 6, v[218:219]
	v_lshl_add_u64 v[4:5], v[2:3], 0, v[4:5]
	global_store_dword v[4:5], v10, off
	v_lshlrev_b64 v[4:5], 6, v[138:139]
	v_lshl_add_u64 v[4:5], v[2:3], 0, v[4:5]
	global_store_dword v[4:5], v11, off
	v_lshlrev_b64 v[4:5], 6, v[140:141]
	v_lshl_add_u64 v[4:5], v[2:3], 0, v[4:5]
	global_store_dword v[4:5], v13, off
	v_lshlrev_b64 v[4:5], 6, v[114:115]
	s_waitcnt lgkmcnt(3)
	v_add_f32_e32 v6, v6, v14
	v_lshl_add_u64 v[4:5], v[2:3], 0, v[4:5]
	global_store_dword v[4:5], v6, off
	v_lshlrev_b64 v[4:5], 6, v[116:117]
	s_waitcnt lgkmcnt(2)
	v_add_f32_e32 v7, v7, v15
	v_lshl_add_u64 v[4:5], v[2:3], 0, v[4:5]
	global_store_dword v[4:5], v7, off
	v_lshlrev_b64 v[4:5], 6, v[46:47]
	s_waitcnt lgkmcnt(1)
	v_add_f32_e32 v8, v8, v16
	v_lshl_add_u64 v[4:5], v[2:3], 0, v[4:5]
	global_store_dword v[4:5], v8, off
	v_lshlrev_b64 v[4:5], 6, v[48:49]
	s_waitcnt lgkmcnt(0)
	v_add_f32_e32 v12, v12, v17
	v_lshl_add_u64 v[2:3], v[2:3], 0, v[4:5]
	global_store_dword v[2:3], v12, off
